# conv-epilogue edge rows stored write-through; leader write-back also skipped after the up GEMM
# speedup vs baseline: 1.0135x; 1.0052x over previous
.Lce_entry:
	s_nop 7
	v_readfirstlane_b32 s4, v0
	v_and_b32_e32 v242, 15, v0
	v_bfe_u32 v243, v0, 4, 2
	s_lshr_b32 s4, s4, 6
	s_and_b32 s4, s4, 7
	s_lshr_b32 s98, s4, 2
	s_and_b32 s99, s4, 3
	s_lshl_b32 s99, s99, 5
	v_lshl_add_u32 v220, v243, 3, s99
	s_lshl_b32 s5, s14, 7
	v_add_lshl_u32 v245, v220, s5, 2
	v_add_u32_e32 v246, 0x2c00, v245
	v_readlane_b32 s10, v250, 7
	v_readlane_b32 s11, v250, 8
	v_readlane_b32 s4, v250, 9
	v_readlane_b32 s5, v250, 10
	s_nop 1
	s_add_u32 s12, s10, 0x5800
	s_addc_u32 s13, s11, 0
	s_add_u32 s100, s10, 0xb000
	s_addc_u32 s101, s11, 0
	s_nop 2
	global_load_dwordx4 v[116:119], v245, s[10:11]
	global_load_dwordx4 v[120:123], v245, s[12:13]
	global_load_dwordx4 v[124:127], v245, s[100:101]
	global_load_dwordx4 v[128:131], v245, s[4:5]
	global_load_dwordx4 v[132:135], v246, s[10:11]
	global_load_dwordx4 v[136:139], v246, s[12:13]
	global_load_dwordx4 v[140:143], v246, s[100:101]
	global_load_dwordx4 v[144:147], v246, s[4:5]
	s_mul_i32 s4, s18, 0x16000
	s_lshl_b32 s5, s14, 10
	s_add_u32 s4, s4, s5
	s_add_u32 s10, s88, 0x14580000
	s_addc_u32 s11, s89, 0
	s_add_u32 s10, s10, s4
	s_addc_u32 s11, s11, 0
	s_mul_i32 s4, s98, 12
	v_subrev_u32_e32 v247, s4, v242
	v_mul_u32_u24_e32 v247, 0x5800, v247
	v_lshl_add_u32 v247, v220, 2, v247
	s_cmp_eq_u32 s98, 0
	s_cbranch_scc0 .Lce_edge_hi
	s_mov_b32 exec_lo, 0x30003
	s_mov_b32 exec_hi, 0x30003
	global_store_dwordx4 v247, v[160:163], s[10:11] offset:0 sc1
	global_store_dwordx4 v247, v[64:67], s[10:11] offset:16 sc1
	global_store_dwordx4 v247, v[156:159], s[10:11] offset:512 sc1
	global_store_dwordx4 v247, v[60:63], s[10:11] offset:528 sc1
	s_branch .Lce_edge_done
.Lce_edge_hi:
	s_mov_b32 exec_lo, 0xc000c000
	s_mov_b32 exec_hi, 0xc000c000
	global_store_dwordx4 v247, v[68:71], s[10:11] offset:0 sc1
	global_store_dwordx4 v247, v[4:7], s[10:11] offset:16 sc1
	global_store_dwordx4 v247, v[72:75], s[10:11] offset:512 sc1
	global_store_dwordx4 v247, v[8:11], s[10:11] offset:528 sc1

.Lxb_leader:
	v_readlane_b32 s98, v252, 2
	s_nop 0
	s_sub_i32 s98, s98, 4
	s_cmp_lt_i32 s98, 0
	s_cbranch_scc1 .Lxb_flush
	s_mul_i32 s99, s98, 0x1746
	s_lshr_b32 s99, s99, 16
	s_mul_i32 s99, s99, 11
	s_sub_i32 s98, s98, s99
	s_lshl_b32 s98, 1, s98
	s_and_b32 s98, s98, 0x6e0
	s_cmp_lg_u32 s98, 0
	s_cbranch_scc1 .Lxb_noflush
